# speedup vs baseline: 1.0684x; 1.0124x over previous
.LBB0_255:
	s_or_b64 exec, exec, s[40:41]
	v_sub_f32_e32 v0, v249, v153
	v_cmp_lt_f32_e32 vcc, v0, v211
	s_cmp_eq_u64 vcc, exec
	s_cbranch_scc1 .LBB0_257
	s_mov_b64 s[40:41], -1
	s_cbranch_execz .LBB0_258
	s_branch .LBB0_259

.LBB0_261:
	v_add_f32_e32 v0, v153, v248
	v_cmp_lt_f32_e32 vcc, v0, v211
	s_and_b64 s[40:41], vcc, exec

.LBB0_273:
	s_or_b64 exec, exec, s[42:43]
	v_sub_f32_e32 v177, v249, v153
	v_cmp_lt_f32_e32 vcc, v177, v211
	s_cmp_eq_u64 vcc, exec
	s_cbranch_scc1 .LBB0_275
	s_mov_b64 s[42:43], -1
	s_cbranch_execz .LBB0_276
	s_branch .LBB0_277

.LBB0_279:
	v_add_f32_e32 v34, v153, v248
	v_cmp_lt_f32_e32 vcc, v34, v211
	s_and_b64 s[42:43], vcc, exec

; DI_ float bf_lo(unsigned w) { return __uint_as_float(w << 16); }
; DI_ float bf_hi(unsigned w) { return __uint_as_float(w & 0xffff0000u); }
; template <int NS>
; DI_ void skinny_pass_bf16(const bf16_t* XBrows, int nrows, const float* WsT, float* sk_out, int gw, int NGW, int lane) {
;     for (int row = gw; row < nrows; row += 4 * NGW) {
;         float v[4][16];
; #pragma unroll
;         for (int r = 0; r < 4; ++r) { const int rr = row + r * NGW < nrows ? row + r * NGW : row; const u32x2* rp = (const u32x2*)(XBrows + (size_t)rr * D) + lane;
; #pragma unroll
;             for (int j = 0; j < 4; ++j) { const u32x2 w = rp[64 * j]; v[r][4 * j] = bf_lo(w.x); v[r][4 * j + 1] = bf_hi(w.x); v[r][4 * j + 2] = bf_lo(w.y); v[r][4 * j + 3] = bf_hi(w.y); } }
; #pragma unroll 1
;         for (int grp = 0; grp < NS / 8; ++grp) {
;             float a[4][8];
; #pragma unroll
;             for (int jc = 0; jc < 8; ++jc) {
;                 const float* wp = WsT + (8 * grp + jc) * WST + 4 * lane; float s0 = 0.f, s1 = 0.f, s2 = 0.f, s3 = 0.f;
; #pragma unroll
;                 for (int j = 0; j < 4; ++j) { const f32x4 w = *(const f32x4*)(wp + 256 * j);
;                     s0 += (v[0][4 * j] * w[0] + v[0][4 * j + 1] * w[1]) + (v[0][4 * j + 2] * w[2] + v[0][4 * j + 3] * w[3]);
;                     s1 += (v[1][4 * j] * w[0] + v[1][4 * j + 1] * w[1]) + (v[1][4 * j + 2] * w[2] + v[1][4 * j + 3] * w[3]);
;                     s2 += (v[2][4 * j] * w[0] + v[2][4 * j + 1] * w[1]) + (v[2][4 * j + 2] * w[2] + v[2][4 * j + 3] * w[3]);
;                     s3 += (v[3][4 * j] * w[0] + v[3][4 * j + 1] * w[1]) + (v[3][4 * j + 2] * w[2] + v[3][4 * j + 3] * w[3]); }
;                 a[0][jc] = s0; a[1][jc] = s1; a[2][jc] = s2; a[3][jc] = s3;
;             }
.LBB0_468:
	s_or_b64 exec, exec, s[6:7]
	v_mov_b32_e32 v0, v187
	s_xor_b64 s[62:63], s[0:1], -1
	s_waitcnt lgkmcnt(0)
	s_barrier
	s_nop 0
	v_readfirstlane_b32 s0, v0
	s_ashr_i32 s4, s0, 6
	s_add_i32 s64, s4, s60
	s_cmpk_gt_i32 s64, 0x3fff
	s_cbranch_scc1 .LBB0_482
	s_lshr_b32 s5, s4, 1
	s_and_b32 s6, s4, 1
	s_lshl_b32 s7, s2, 6
	s_lshl_b32 s5, s5, 4
	s_add_i32 s7, s7, s5
	s_lshl_b32 s6, s6, 4
	v_and_b32_e32 v1, 63, v0
	v_and_b32_e32 v2, 15, v1
	v_lshrrev_b32_e32 v3, 4, v1
	v_add_u32_e32 v4, s7, v2
	v_lshlrev_b32_e32 v4, 11, v4
	v_lshl_add_u32 v4, v3, 9, v4
	v_mov_b32_e32 v5, 0
	v_lshl_add_u64 v[6:7], s[54:55], 0, v[4:5]
	v_add_u32_e32 v8, s6, v2
	v_mul_u32_u24_e32 v9, 0x1010, v8
	v_lshl_add_u32 v9, v3, 10, v9
	v_lshl_add_u32 v10, v3, 2, s7
	v_lshlrev_b32_e32 v10, 7, v10
	v_lshl_add_u32 v10, v8, 2, v10
	v_mov_b32_e32 v11, 0
	v_lshl_add_u64 v[10:11], s[28:29], 0, v[10:11]
	v_mov_b32_e32 v12, 0
	v_mov_b32_e32 v13, 0
	v_mov_b32_e32 v14, 0
	v_mov_b32_e32 v15, 0
	v_mov_b32_e32 v16, 0
	v_mov_b32_e32 v17, 0
	v_mov_b32_e32 v18, 0
	v_mov_b32_e32 v19, 0
	global_load_dwordx4 v[20:23], v[6:7], off
	global_load_dwordx4 v[24:27], v[6:7], off offset:16
	global_load_dwordx4 v[28:31], v[6:7], off offset:32
	global_load_dwordx4 v[32:35], v[6:7], off offset:48
	global_load_dwordx4 v[50:53], v[6:7], off offset:64
	global_load_dwordx4 v[54:57], v[6:7], off offset:80
	global_load_dwordx4 v[58:61], v[6:7], off offset:96
	global_load_dwordx4 v[62:65], v[6:7], off offset:112
	ds_read_b128 v[66:69], v9
	ds_read_b128 v[70:73], v9 offset:16
	ds_read_b128 v[74:77], v9 offset:32
	ds_read_b128 v[78:81], v9 offset:48
	ds_read_b128 v[82:85], v9 offset:64
	ds_read_b128 v[86:89], v9 offset:80
	ds_read_b128 v[90:93], v9 offset:96
	ds_read_b128 v[94:97], v9 offset:112
	global_load_dwordx4 v[130:133], v[6:7], off offset:128
	global_load_dwordx4 v[134:137], v[6:7], off offset:144
	global_load_dwordx4 v[138:141], v[6:7], off offset:160
	global_load_dwordx4 v[142:145], v[6:7], off offset:176
	ds_read_b128 v[98:101], v9 offset:128
	ds_read_b128 v[102:105], v9 offset:144
	ds_read_b128 v[106:109], v9 offset:160
	ds_read_b128 v[110:113], v9 offset:176
	ds_read_b128 v[114:117], v9 offset:192
	ds_read_b128 v[118:121], v9 offset:208
	ds_read_b128 v[122:125], v9 offset:224
	ds_read_b128 v[126:129], v9 offset:240
	s_waitcnt vmcnt(8)
	s_waitcnt lgkmcnt(8)
	v_lshlrev_b32_e32 v36, 16, v20
	v_and_b32_e32 v37, 0xffff0000, v20
	v_lshlrev_b32_e32 v38, 16, v21
	v_mfma_f32_16x16x4_f32 v[12:15], v36, v66, v[12:15]
	v_and_b32_e32 v39, 0xffff0000, v21
	v_mfma_f32_16x16x4_f32 v[16:19], v37, v67, v[16:19]
	v_lshlrev_b32_e32 v36, 16, v22
	v_mfma_f32_16x16x4_f32 v[12:15], v38, v68, v[12:15]
	v_and_b32_e32 v37, 0xffff0000, v22
	v_mfma_f32_16x16x4_f32 v[16:19], v39, v69, v[16:19]
	v_lshlrev_b32_e32 v38, 16, v23
	v_mfma_f32_16x16x4_f32 v[12:15], v36, v70, v[12:15]
	v_and_b32_e32 v39, 0xffff0000, v23
	v_mfma_f32_16x16x4_f32 v[16:19], v37, v71, v[16:19]
	v_lshlrev_b32_e32 v36, 16, v24
	v_mfma_f32_16x16x4_f32 v[12:15], v38, v72, v[12:15]
	v_and_b32_e32 v37, 0xffff0000, v24
	v_mfma_f32_16x16x4_f32 v[16:19], v39, v73, v[16:19]
	v_lshlrev_b32_e32 v38, 16, v25
	v_mfma_f32_16x16x4_f32 v[12:15], v36, v74, v[12:15]
	v_and_b32_e32 v39, 0xffff0000, v25
	v_mfma_f32_16x16x4_f32 v[16:19], v37, v75, v[16:19]
	v_lshlrev_b32_e32 v36, 16, v26
	v_mfma_f32_16x16x4_f32 v[12:15], v38, v76, v[12:15]
	v_and_b32_e32 v37, 0xffff0000, v26
	v_mfma_f32_16x16x4_f32 v[16:19], v39, v77, v[16:19]
	v_lshlrev_b32_e32 v38, 16, v27
	v_mfma_f32_16x16x4_f32 v[12:15], v36, v78, v[12:15]
	v_and_b32_e32 v39, 0xffff0000, v27
	v_mfma_f32_16x16x4_f32 v[16:19], v37, v79, v[16:19]
	v_lshlrev_b32_e32 v36, 16, v28
	v_mfma_f32_16x16x4_f32 v[12:15], v38, v80, v[12:15]
	v_and_b32_e32 v37, 0xffff0000, v28
	v_mfma_f32_16x16x4_f32 v[16:19], v39, v81, v[16:19]
	v_lshlrev_b32_e32 v38, 16, v29
	v_mfma_f32_16x16x4_f32 v[12:15], v36, v82, v[12:15]
	v_and_b32_e32 v39, 0xffff0000, v29
	v_mfma_f32_16x16x4_f32 v[16:19], v37, v83, v[16:19]
	v_lshlrev_b32_e32 v36, 16, v30
	v_mfma_f32_16x16x4_f32 v[12:15], v38, v84, v[12:15]
	v_and_b32_e32 v37, 0xffff0000, v30
	v_mfma_f32_16x16x4_f32 v[16:19], v39, v85, v[16:19]
	v_lshlrev_b32_e32 v38, 16, v31
	v_mfma_f32_16x16x4_f32 v[12:15], v36, v86, v[12:15]
	v_and_b32_e32 v39, 0xffff0000, v31
	v_mfma_f32_16x16x4_f32 v[16:19], v37, v87, v[16:19]
	v_lshlrev_b32_e32 v36, 16, v32
	v_mfma_f32_16x16x4_f32 v[12:15], v38, v88, v[12:15]
	v_and_b32_e32 v37, 0xffff0000, v32
	v_mfma_f32_16x16x4_f32 v[16:19], v39, v89, v[16:19]
	v_lshlrev_b32_e32 v38, 16, v33
	v_mfma_f32_16x16x4_f32 v[12:15], v36, v90, v[12:15]
	v_and_b32_e32 v39, 0xffff0000, v33
	v_mfma_f32_16x16x4_f32 v[16:19], v37, v91, v[16:19]
	v_lshlrev_b32_e32 v36, 16, v34
	v_mfma_f32_16x16x4_f32 v[12:15], v38, v92, v[12:15]
	v_and_b32_e32 v37, 0xffff0000, v34
	v_mfma_f32_16x16x4_f32 v[16:19], v39, v93, v[16:19]
	v_lshlrev_b32_e32 v38, 16, v35
	v_mfma_f32_16x16x4_f32 v[12:15], v36, v94, v[12:15]
	v_and_b32_e32 v39, 0xffff0000, v35
	v_mfma_f32_16x16x4_f32 v[16:19], v37, v95, v[16:19]
	s_nop 0
	v_mfma_f32_16x16x4_f32 v[12:15], v38, v96, v[12:15]
	s_nop 0
	v_mfma_f32_16x16x4_f32 v[16:19], v39, v97, v[16:19]
	global_load_dwordx4 v[20:23], v[6:7], off offset:192
	global_load_dwordx4 v[24:27], v[6:7], off offset:208
	global_load_dwordx4 v[28:31], v[6:7], off offset:224
	global_load_dwordx4 v[32:35], v[6:7], off offset:240
	ds_read_b128 v[66:69], v9 offset:256
	ds_read_b128 v[70:73], v9 offset:272
	ds_read_b128 v[74:77], v9 offset:288
	ds_read_b128 v[78:81], v9 offset:304
	ds_read_b128 v[82:85], v9 offset:320
	ds_read_b128 v[86:89], v9 offset:336
	ds_read_b128 v[90:93], v9 offset:352
	ds_read_b128 v[94:97], v9 offset:368
	s_waitcnt vmcnt(8)
; DI_ float bf_lo(unsigned w) { return __uint_as_float(w << 16); }
; DI_ float bf_hi(unsigned w) { return __uint_as_float(w & 0xffff0000u); }
; template <int NS>
; DI_ void skinny_pass_bf16(const bf16_t* XBrows, int nrows, const float* WsT, float* sk_out, int gw, int NGW, int lane) {
;     for (int row = gw; row < nrows; row += 4 * NGW) {
;         float v[4][16];
; #pragma unroll
;         for (int r = 0; r < 4; ++r) { const int rr = row + r * NGW < nrows ? row + r * NGW : row; const u32x2* rp = (const u32x2*)(XBrows + (size_t)rr * D) + lane;
; #pragma unroll
;             for (int j = 0; j < 4; ++j) { const u32x2 w = rp[64 * j]; v[r][4 * j] = bf_lo(w.x); v[r][4 * j + 1] = bf_hi(w.x); v[r][4 * j + 2] = bf_lo(w.y); v[r][4 * j + 3] = bf_hi(w.y); } }
; #pragma unroll 1
;         for (int grp = 0; grp < NS / 8; ++grp) {
;             float a[4][8];
; #pragma unroll
;             for (int jc = 0; jc < 8; ++jc) {
;                 const float* wp = WsT + (8 * grp + jc) * WST + 4 * lane; float s0 = 0.f, s1 = 0.f, s2 = 0.f, s3 = 0.f;
; #pragma unroll
;                 for (int j = 0; j < 4; ++j) { const f32x4 w = *(const f32x4*)(wp + 256 * j);
;                     s0 += (v[0][4 * j] * w[0] + v[0][4 * j + 1] * w[1]) + (v[0][4 * j + 2] * w[2] + v[0][4 * j + 3] * w[3]);
;                     s1 += (v[1][4 * j] * w[0] + v[1][4 * j + 1] * w[1]) + (v[1][4 * j + 2] * w[2] + v[1][4 * j + 3] * w[3]);
;                     s2 += (v[2][4 * j] * w[0] + v[2][4 * j + 1] * w[1]) + (v[2][4 * j + 2] * w[2] + v[2][4 * j + 3] * w[3]);
;                     s3 += (v[3][4 * j] * w[0] + v[3][4 * j + 1] * w[1]) + (v[3][4 * j + 2] * w[2] + v[3][4 * j + 3] * w[3]); }
;                 a[0][jc] = s0; a[1][jc] = s1; a[2][jc] = s2; a[3][jc] = s3;
;             }
	s_waitcnt lgkmcnt(8)
	v_lshlrev_b32_e32 v36, 16, v50
	v_and_b32_e32 v37, 0xffff0000, v50
	v_lshlrev_b32_e32 v38, 16, v51
	v_mfma_f32_16x16x4_f32 v[12:15], v36, v98, v[12:15]
	v_and_b32_e32 v39, 0xffff0000, v51
	v_mfma_f32_16x16x4_f32 v[16:19], v37, v99, v[16:19]
	v_lshlrev_b32_e32 v36, 16, v52
	v_mfma_f32_16x16x4_f32 v[12:15], v38, v100, v[12:15]
	v_and_b32_e32 v37, 0xffff0000, v52
	v_mfma_f32_16x16x4_f32 v[16:19], v39, v101, v[16:19]
	v_lshlrev_b32_e32 v38, 16, v53
	v_mfma_f32_16x16x4_f32 v[12:15], v36, v102, v[12:15]
	v_and_b32_e32 v39, 0xffff0000, v53
	v_mfma_f32_16x16x4_f32 v[16:19], v37, v103, v[16:19]
	v_lshlrev_b32_e32 v36, 16, v54
	v_mfma_f32_16x16x4_f32 v[12:15], v38, v104, v[12:15]
	v_and_b32_e32 v37, 0xffff0000, v54
	v_mfma_f32_16x16x4_f32 v[16:19], v39, v105, v[16:19]
	v_lshlrev_b32_e32 v38, 16, v55
	v_mfma_f32_16x16x4_f32 v[12:15], v36, v106, v[12:15]
	v_and_b32_e32 v39, 0xffff0000, v55
	v_mfma_f32_16x16x4_f32 v[16:19], v37, v107, v[16:19]
	v_lshlrev_b32_e32 v36, 16, v56
	v_mfma_f32_16x16x4_f32 v[12:15], v38, v108, v[12:15]
	v_and_b32_e32 v37, 0xffff0000, v56
	v_mfma_f32_16x16x4_f32 v[16:19], v39, v109, v[16:19]
	v_lshlrev_b32_e32 v38, 16, v57
	v_mfma_f32_16x16x4_f32 v[12:15], v36, v110, v[12:15]
	v_and_b32_e32 v39, 0xffff0000, v57
	v_mfma_f32_16x16x4_f32 v[16:19], v37, v111, v[16:19]
	v_lshlrev_b32_e32 v36, 16, v58
	v_mfma_f32_16x16x4_f32 v[12:15], v38, v112, v[12:15]
	v_and_b32_e32 v37, 0xffff0000, v58
	v_mfma_f32_16x16x4_f32 v[16:19], v39, v113, v[16:19]
	v_lshlrev_b32_e32 v38, 16, v59
	v_mfma_f32_16x16x4_f32 v[12:15], v36, v114, v[12:15]
	v_and_b32_e32 v39, 0xffff0000, v59
	v_mfma_f32_16x16x4_f32 v[16:19], v37, v115, v[16:19]
	v_lshlrev_b32_e32 v36, 16, v60
	v_mfma_f32_16x16x4_f32 v[12:15], v38, v116, v[12:15]
	v_and_b32_e32 v37, 0xffff0000, v60
	v_mfma_f32_16x16x4_f32 v[16:19], v39, v117, v[16:19]
	v_lshlrev_b32_e32 v38, 16, v61
	v_mfma_f32_16x16x4_f32 v[12:15], v36, v118, v[12:15]
	v_and_b32_e32 v39, 0xffff0000, v61
	v_mfma_f32_16x16x4_f32 v[16:19], v37, v119, v[16:19]
	v_lshlrev_b32_e32 v36, 16, v62
	v_mfma_f32_16x16x4_f32 v[12:15], v38, v120, v[12:15]
	v_and_b32_e32 v37, 0xffff0000, v62
	v_mfma_f32_16x16x4_f32 v[16:19], v39, v121, v[16:19]
	v_lshlrev_b32_e32 v38, 16, v63
	v_mfma_f32_16x16x4_f32 v[12:15], v36, v122, v[12:15]
	v_and_b32_e32 v39, 0xffff0000, v63
	v_mfma_f32_16x16x4_f32 v[16:19], v37, v123, v[16:19]
	v_lshlrev_b32_e32 v36, 16, v64
	v_mfma_f32_16x16x4_f32 v[12:15], v38, v124, v[12:15]
	v_and_b32_e32 v37, 0xffff0000, v64
	v_mfma_f32_16x16x4_f32 v[16:19], v39, v125, v[16:19]
	v_lshlrev_b32_e32 v38, 16, v65
	v_mfma_f32_16x16x4_f32 v[12:15], v36, v126, v[12:15]
	v_and_b32_e32 v39, 0xffff0000, v65
	v_mfma_f32_16x16x4_f32 v[16:19], v37, v127, v[16:19]
	s_nop 0
	v_mfma_f32_16x16x4_f32 v[12:15], v38, v128, v[12:15]
	s_nop 0
	v_mfma_f32_16x16x4_f32 v[16:19], v39, v129, v[16:19]
	global_load_dwordx4 v[50:53], v[6:7], off offset:256
	global_load_dwordx4 v[54:57], v[6:7], off offset:272
	global_load_dwordx4 v[58:61], v[6:7], off offset:288
	global_load_dwordx4 v[62:65], v[6:7], off offset:304
	ds_read_b128 v[98:101], v9 offset:384
	ds_read_b128 v[102:105], v9 offset:400
	ds_read_b128 v[106:109], v9 offset:416
	ds_read_b128 v[110:113], v9 offset:432
	ds_read_b128 v[114:117], v9 offset:448
	ds_read_b128 v[118:121], v9 offset:464
	ds_read_b128 v[122:125], v9 offset:480
	ds_read_b128 v[126:129], v9 offset:496
	s_waitcnt vmcnt(8)
	s_waitcnt lgkmcnt(8)
	v_lshlrev_b32_e32 v36, 16, v130
	v_and_b32_e32 v37, 0xffff0000, v130
	v_lshlrev_b32_e32 v38, 16, v131
	v_mfma_f32_16x16x4_f32 v[12:15], v36, v66, v[12:15]
	v_and_b32_e32 v39, 0xffff0000, v131
	v_mfma_f32_16x16x4_f32 v[16:19], v37, v67, v[16:19]
	v_lshlrev_b32_e32 v36, 16, v132
	v_mfma_f32_16x16x4_f32 v[12:15], v38, v68, v[12:15]
	v_and_b32_e32 v37, 0xffff0000, v132
	v_mfma_f32_16x16x4_f32 v[16:19], v39, v69, v[16:19]
	v_lshlrev_b32_e32 v38, 16, v133
	v_mfma_f32_16x16x4_f32 v[12:15], v36, v70, v[12:15]
	v_and_b32_e32 v39, 0xffff0000, v133
	v_mfma_f32_16x16x4_f32 v[16:19], v37, v71, v[16:19]
	v_lshlrev_b32_e32 v36, 16, v134
	v_mfma_f32_16x16x4_f32 v[12:15], v38, v72, v[12:15]
	v_and_b32_e32 v37, 0xffff0000, v134
	v_mfma_f32_16x16x4_f32 v[16:19], v39, v73, v[16:19]
	v_lshlrev_b32_e32 v38, 16, v135
	v_mfma_f32_16x16x4_f32 v[12:15], v36, v74, v[12:15]
	v_and_b32_e32 v39, 0xffff0000, v135
	v_mfma_f32_16x16x4_f32 v[16:19], v37, v75, v[16:19]
	v_lshlrev_b32_e32 v36, 16, v136
	v_mfma_f32_16x16x4_f32 v[12:15], v38, v76, v[12:15]
	v_and_b32_e32 v37, 0xffff0000, v136
	v_mfma_f32_16x16x4_f32 v[16:19], v39, v77, v[16:19]
	v_lshlrev_b32_e32 v38, 16, v137
	v_mfma_f32_16x16x4_f32 v[12:15], v36, v78, v[12:15]
	v_and_b32_e32 v39, 0xffff0000, v137
	v_mfma_f32_16x16x4_f32 v[16:19], v37, v79, v[16:19]
	v_lshlrev_b32_e32 v36, 16, v138
	v_mfma_f32_16x16x4_f32 v[12:15], v38, v80, v[12:15]
	v_and_b32_e32 v37, 0xffff0000, v138
	v_mfma_f32_16x16x4_f32 v[16:19], v39, v81, v[16:19]
	v_lshlrev_b32_e32 v38, 16, v139
	v_mfma_f32_16x16x4_f32 v[12:15], v36, v82, v[12:15]
	v_and_b32_e32 v39, 0xffff0000, v139
	v_mfma_f32_16x16x4_f32 v[16:19], v37, v83, v[16:19]
	v_lshlrev_b32_e32 v36, 16, v140
	v_mfma_f32_16x16x4_f32 v[12:15], v38, v84, v[12:15]
	v_and_b32_e32 v37, 0xffff0000, v140
	v_mfma_f32_16x16x4_f32 v[16:19], v39, v85, v[16:19]
	v_lshlrev_b32_e32 v38, 16, v141
	v_mfma_f32_16x16x4_f32 v[12:15], v36, v86, v[12:15]
	v_and_b32_e32 v39, 0xffff0000, v141
	v_mfma_f32_16x16x4_f32 v[16:19], v37, v87, v[16:19]
	v_lshlrev_b32_e32 v36, 16, v142
	v_mfma_f32_16x16x4_f32 v[12:15], v38, v88, v[12:15]
	v_and_b32_e32 v37, 0xffff0000, v142
	v_mfma_f32_16x16x4_f32 v[16:19], v39, v89, v[16:19]
	v_lshlrev_b32_e32 v38, 16, v143
	v_mfma_f32_16x16x4_f32 v[12:15], v36, v90, v[12:15]
	v_and_b32_e32 v39, 0xffff0000, v143
	v_mfma_f32_16x16x4_f32 v[16:19], v37, v91, v[16:19]
	v_lshlrev_b32_e32 v36, 16, v144
	v_mfma_f32_16x16x4_f32 v[12:15], v38, v92, v[12:15]
	v_and_b32_e32 v37, 0xffff0000, v144
	v_mfma_f32_16x16x4_f32 v[16:19], v39, v93, v[16:19]
	v_lshlrev_b32_e32 v38, 16, v145
	v_mfma_f32_16x16x4_f32 v[12:15], v36, v94, v[12:15]
	v_and_b32_e32 v39, 0xffff0000, v145
	v_mfma_f32_16x16x4_f32 v[16:19], v37, v95, v[16:19]
	s_nop 0
	v_mfma_f32_16x16x4_f32 v[12:15], v38, v96, v[12:15]
	s_nop 0
	v_mfma_f32_16x16x4_f32 v[16:19], v39, v97, v[16:19]
	global_load_dwordx4 v[130:133], v[6:7], off offset:320
	global_load_dwordx4 v[134:137], v[6:7], off offset:336
	global_load_dwordx4 v[138:141], v[6:7], off offset:352
	global_load_dwordx4 v[142:145], v[6:7], off offset:368
	ds_read_b128 v[66:69], v9 offset:512
	ds_read_b128 v[70:73], v9 offset:528
	ds_read_b128 v[74:77], v9 offset:544
	ds_read_b128 v[78:81], v9 offset:560
	ds_read_b128 v[82:85], v9 offset:576
	ds_read_b128 v[86:89], v9 offset:592
	ds_read_b128 v[90:93], v9 offset:608
	ds_read_b128 v[94:97], v9 offset:624
	s_waitcnt vmcnt(8)
; DI_ float bf_lo(unsigned w) { return __uint_as_float(w << 16); }
; DI_ float bf_hi(unsigned w) { return __uint_as_float(w & 0xffff0000u); }
; template <int NS>
; DI_ void skinny_pass_bf16(const bf16_t* XBrows, int nrows, const float* WsT, float* sk_out, int gw, int NGW, int lane) {
;     for (int row = gw; row < nrows; row += 4 * NGW) {
;         float v[4][16];
; #pragma unroll
;         for (int r = 0; r < 4; ++r) { const int rr = row + r * NGW < nrows ? row + r * NGW : row; const u32x2* rp = (const u32x2*)(XBrows + (size_t)rr * D) + lane;
; #pragma unroll
;             for (int j = 0; j < 4; ++j) { const u32x2 w = rp[64 * j]; v[r][4 * j] = bf_lo(w.x); v[r][4 * j + 1] = bf_hi(w.x); v[r][4 * j + 2] = bf_lo(w.y); v[r][4 * j + 3] = bf_hi(w.y); } }
; #pragma unroll 1
;         for (int grp = 0; grp < NS / 8; ++grp) {
;             float a[4][8];
; #pragma unroll
;             for (int jc = 0; jc < 8; ++jc) {
;                 const float* wp = WsT + (8 * grp + jc) * WST + 4 * lane; float s0 = 0.f, s1 = 0.f, s2 = 0.f, s3 = 0.f;
; #pragma unroll
;                 for (int j = 0; j < 4; ++j) { const f32x4 w = *(const f32x4*)(wp + 256 * j);
;                     s0 += (v[0][4 * j] * w[0] + v[0][4 * j + 1] * w[1]) + (v[0][4 * j + 2] * w[2] + v[0][4 * j + 3] * w[3]);
;                     s1 += (v[1][4 * j] * w[0] + v[1][4 * j + 1] * w[1]) + (v[1][4 * j + 2] * w[2] + v[1][4 * j + 3] * w[3]);
;                     s2 += (v[2][4 * j] * w[0] + v[2][4 * j + 1] * w[1]) + (v[2][4 * j + 2] * w[2] + v[2][4 * j + 3] * w[3]);
;                     s3 += (v[3][4 * j] * w[0] + v[3][4 * j + 1] * w[1]) + (v[3][4 * j + 2] * w[2] + v[3][4 * j + 3] * w[3]); }
;                 a[0][jc] = s0; a[1][jc] = s1; a[2][jc] = s2; a[3][jc] = s3;
;             }
	s_waitcnt lgkmcnt(8)
	v_lshlrev_b32_e32 v36, 16, v20
	v_and_b32_e32 v37, 0xffff0000, v20
	v_lshlrev_b32_e32 v38, 16, v21
	v_mfma_f32_16x16x4_f32 v[12:15], v36, v98, v[12:15]
	v_and_b32_e32 v39, 0xffff0000, v21
	v_mfma_f32_16x16x4_f32 v[16:19], v37, v99, v[16:19]
	v_lshlrev_b32_e32 v36, 16, v22
	v_mfma_f32_16x16x4_f32 v[12:15], v38, v100, v[12:15]
	v_and_b32_e32 v37, 0xffff0000, v22
	v_mfma_f32_16x16x4_f32 v[16:19], v39, v101, v[16:19]
	v_lshlrev_b32_e32 v38, 16, v23
	v_mfma_f32_16x16x4_f32 v[12:15], v36, v102, v[12:15]
	v_and_b32_e32 v39, 0xffff0000, v23
	v_mfma_f32_16x16x4_f32 v[16:19], v37, v103, v[16:19]
	v_lshlrev_b32_e32 v36, 16, v24
	v_mfma_f32_16x16x4_f32 v[12:15], v38, v104, v[12:15]
	v_and_b32_e32 v37, 0xffff0000, v24
	v_mfma_f32_16x16x4_f32 v[16:19], v39, v105, v[16:19]
	v_lshlrev_b32_e32 v38, 16, v25
	v_mfma_f32_16x16x4_f32 v[12:15], v36, v106, v[12:15]
	v_and_b32_e32 v39, 0xffff0000, v25
	v_mfma_f32_16x16x4_f32 v[16:19], v37, v107, v[16:19]
	v_lshlrev_b32_e32 v36, 16, v26
	v_mfma_f32_16x16x4_f32 v[12:15], v38, v108, v[12:15]
	v_and_b32_e32 v37, 0xffff0000, v26
	v_mfma_f32_16x16x4_f32 v[16:19], v39, v109, v[16:19]
	v_lshlrev_b32_e32 v38, 16, v27
	v_mfma_f32_16x16x4_f32 v[12:15], v36, v110, v[12:15]
	v_and_b32_e32 v39, 0xffff0000, v27
	v_mfma_f32_16x16x4_f32 v[16:19], v37, v111, v[16:19]
	v_lshlrev_b32_e32 v36, 16, v28
	v_mfma_f32_16x16x4_f32 v[12:15], v38, v112, v[12:15]
	v_and_b32_e32 v37, 0xffff0000, v28
	v_mfma_f32_16x16x4_f32 v[16:19], v39, v113, v[16:19]
	v_lshlrev_b32_e32 v38, 16, v29
	v_mfma_f32_16x16x4_f32 v[12:15], v36, v114, v[12:15]
	v_and_b32_e32 v39, 0xffff0000, v29
	v_mfma_f32_16x16x4_f32 v[16:19], v37, v115, v[16:19]
	v_lshlrev_b32_e32 v36, 16, v30
	v_mfma_f32_16x16x4_f32 v[12:15], v38, v116, v[12:15]
	v_and_b32_e32 v37, 0xffff0000, v30
	v_mfma_f32_16x16x4_f32 v[16:19], v39, v117, v[16:19]
	v_lshlrev_b32_e32 v38, 16, v31
	v_mfma_f32_16x16x4_f32 v[12:15], v36, v118, v[12:15]
	v_and_b32_e32 v39, 0xffff0000, v31
	v_mfma_f32_16x16x4_f32 v[16:19], v37, v119, v[16:19]
	v_lshlrev_b32_e32 v36, 16, v32
	v_mfma_f32_16x16x4_f32 v[12:15], v38, v120, v[12:15]
	v_and_b32_e32 v37, 0xffff0000, v32
	v_mfma_f32_16x16x4_f32 v[16:19], v39, v121, v[16:19]
	v_lshlrev_b32_e32 v38, 16, v33
	v_mfma_f32_16x16x4_f32 v[12:15], v36, v122, v[12:15]
	v_and_b32_e32 v39, 0xffff0000, v33
	v_mfma_f32_16x16x4_f32 v[16:19], v37, v123, v[16:19]
	v_lshlrev_b32_e32 v36, 16, v34
	v_mfma_f32_16x16x4_f32 v[12:15], v38, v124, v[12:15]
	v_and_b32_e32 v37, 0xffff0000, v34
	v_mfma_f32_16x16x4_f32 v[16:19], v39, v125, v[16:19]
	v_lshlrev_b32_e32 v38, 16, v35
	v_mfma_f32_16x16x4_f32 v[12:15], v36, v126, v[12:15]
	v_and_b32_e32 v39, 0xffff0000, v35
	v_mfma_f32_16x16x4_f32 v[16:19], v37, v127, v[16:19]
	s_nop 0
	v_mfma_f32_16x16x4_f32 v[12:15], v38, v128, v[12:15]
	s_nop 0
	v_mfma_f32_16x16x4_f32 v[16:19], v39, v129, v[16:19]
	global_load_dwordx4 v[20:23], v[6:7], off offset:384
	global_load_dwordx4 v[24:27], v[6:7], off offset:400
	global_load_dwordx4 v[28:31], v[6:7], off offset:416
	global_load_dwordx4 v[32:35], v[6:7], off offset:432
	ds_read_b128 v[98:101], v9 offset:640
	ds_read_b128 v[102:105], v9 offset:656
	ds_read_b128 v[106:109], v9 offset:672
	ds_read_b128 v[110:113], v9 offset:688
	ds_read_b128 v[114:117], v9 offset:704
	ds_read_b128 v[118:121], v9 offset:720
	ds_read_b128 v[122:125], v9 offset:736
	ds_read_b128 v[126:129], v9 offset:752
	s_waitcnt vmcnt(8)
	s_waitcnt lgkmcnt(8)
	v_lshlrev_b32_e32 v36, 16, v50
	v_and_b32_e32 v37, 0xffff0000, v50
	v_lshlrev_b32_e32 v38, 16, v51
	v_mfma_f32_16x16x4_f32 v[12:15], v36, v66, v[12:15]
	v_and_b32_e32 v39, 0xffff0000, v51
	v_mfma_f32_16x16x4_f32 v[16:19], v37, v67, v[16:19]
	v_lshlrev_b32_e32 v36, 16, v52
	v_mfma_f32_16x16x4_f32 v[12:15], v38, v68, v[12:15]
	v_and_b32_e32 v37, 0xffff0000, v52
	v_mfma_f32_16x16x4_f32 v[16:19], v39, v69, v[16:19]
	v_lshlrev_b32_e32 v38, 16, v53
	v_mfma_f32_16x16x4_f32 v[12:15], v36, v70, v[12:15]
	v_and_b32_e32 v39, 0xffff0000, v53
	v_mfma_f32_16x16x4_f32 v[16:19], v37, v71, v[16:19]
	v_lshlrev_b32_e32 v36, 16, v54
	v_mfma_f32_16x16x4_f32 v[12:15], v38, v72, v[12:15]
	v_and_b32_e32 v37, 0xffff0000, v54
	v_mfma_f32_16x16x4_f32 v[16:19], v39, v73, v[16:19]
	v_lshlrev_b32_e32 v38, 16, v55
	v_mfma_f32_16x16x4_f32 v[12:15], v36, v74, v[12:15]
	v_and_b32_e32 v39, 0xffff0000, v55
	v_mfma_f32_16x16x4_f32 v[16:19], v37, v75, v[16:19]
	v_lshlrev_b32_e32 v36, 16, v56
	v_mfma_f32_16x16x4_f32 v[12:15], v38, v76, v[12:15]
	v_and_b32_e32 v37, 0xffff0000, v56
	v_mfma_f32_16x16x4_f32 v[16:19], v39, v77, v[16:19]
	v_lshlrev_b32_e32 v38, 16, v57
	v_mfma_f32_16x16x4_f32 v[12:15], v36, v78, v[12:15]
	v_and_b32_e32 v39, 0xffff0000, v57
	v_mfma_f32_16x16x4_f32 v[16:19], v37, v79, v[16:19]
	v_lshlrev_b32_e32 v36, 16, v58
	v_mfma_f32_16x16x4_f32 v[12:15], v38, v80, v[12:15]
	v_and_b32_e32 v37, 0xffff0000, v58
	v_mfma_f32_16x16x4_f32 v[16:19], v39, v81, v[16:19]
	v_lshlrev_b32_e32 v38, 16, v59
	v_mfma_f32_16x16x4_f32 v[12:15], v36, v82, v[12:15]
	v_and_b32_e32 v39, 0xffff0000, v59
	v_mfma_f32_16x16x4_f32 v[16:19], v37, v83, v[16:19]
	v_lshlrev_b32_e32 v36, 16, v60
	v_mfma_f32_16x16x4_f32 v[12:15], v38, v84, v[12:15]
	v_and_b32_e32 v37, 0xffff0000, v60
	v_mfma_f32_16x16x4_f32 v[16:19], v39, v85, v[16:19]
	v_lshlrev_b32_e32 v38, 16, v61
	v_mfma_f32_16x16x4_f32 v[12:15], v36, v86, v[12:15]
	v_and_b32_e32 v39, 0xffff0000, v61
	v_mfma_f32_16x16x4_f32 v[16:19], v37, v87, v[16:19]
	v_lshlrev_b32_e32 v36, 16, v62
	v_mfma_f32_16x16x4_f32 v[12:15], v38, v88, v[12:15]
	v_and_b32_e32 v37, 0xffff0000, v62
	v_mfma_f32_16x16x4_f32 v[16:19], v39, v89, v[16:19]
	v_lshlrev_b32_e32 v38, 16, v63
	v_mfma_f32_16x16x4_f32 v[12:15], v36, v90, v[12:15]
	v_and_b32_e32 v39, 0xffff0000, v63
	v_mfma_f32_16x16x4_f32 v[16:19], v37, v91, v[16:19]
	v_lshlrev_b32_e32 v36, 16, v64
	v_mfma_f32_16x16x4_f32 v[12:15], v38, v92, v[12:15]
	v_and_b32_e32 v37, 0xffff0000, v64
	v_mfma_f32_16x16x4_f32 v[16:19], v39, v93, v[16:19]
	v_lshlrev_b32_e32 v38, 16, v65
	v_mfma_f32_16x16x4_f32 v[12:15], v36, v94, v[12:15]
	v_and_b32_e32 v39, 0xffff0000, v65
	v_mfma_f32_16x16x4_f32 v[16:19], v37, v95, v[16:19]
	s_nop 0
	v_mfma_f32_16x16x4_f32 v[12:15], v38, v96, v[12:15]
	s_nop 0
	v_mfma_f32_16x16x4_f32 v[16:19], v39, v97, v[16:19]
	global_load_dwordx4 v[50:53], v[6:7], off offset:448
	global_load_dwordx4 v[54:57], v[6:7], off offset:464
	global_load_dwordx4 v[58:61], v[6:7], off offset:480
	global_load_dwordx4 v[62:65], v[6:7], off offset:496
	ds_read_b128 v[66:69], v9 offset:768
	ds_read_b128 v[70:73], v9 offset:784
	ds_read_b128 v[74:77], v9 offset:800
	ds_read_b128 v[78:81], v9 offset:816
	ds_read_b128 v[82:85], v9 offset:832
	ds_read_b128 v[86:89], v9 offset:848
	ds_read_b128 v[90:93], v9 offset:864
	ds_read_b128 v[94:97], v9 offset:880
	s_waitcnt vmcnt(8)
; DI_ float bf_lo(unsigned w) { return __uint_as_float(w << 16); }
; DI_ float bf_hi(unsigned w) { return __uint_as_float(w & 0xffff0000u); }
; template <int NS>
; DI_ void skinny_pass_bf16(const bf16_t* XBrows, int nrows, const float* WsT, float* sk_out, int gw, int NGW, int lane) {
;     for (int row = gw; row < nrows; row += 4 * NGW) {
;         float v[4][16];
; #pragma unroll
;         for (int r = 0; r < 4; ++r) { const int rr = row + r * NGW < nrows ? row + r * NGW : row; const u32x2* rp = (const u32x2*)(XBrows + (size_t)rr * D) + lane;
; #pragma unroll
;             for (int j = 0; j < 4; ++j) { const u32x2 w = rp[64 * j]; v[r][4 * j] = bf_lo(w.x); v[r][4 * j + 1] = bf_hi(w.x); v[r][4 * j + 2] = bf_lo(w.y); v[r][4 * j + 3] = bf_hi(w.y); } }
; #pragma unroll 1
;         for (int grp = 0; grp < NS / 8; ++grp) {
;             float a[4][8];
; #pragma unroll
;             for (int jc = 0; jc < 8; ++jc) {
;                 const float* wp = WsT + (8 * grp + jc) * WST + 4 * lane; float s0 = 0.f, s1 = 0.f, s2 = 0.f, s3 = 0.f;
; #pragma unroll
;                 for (int j = 0; j < 4; ++j) { const f32x4 w = *(const f32x4*)(wp + 256 * j);
;                     s0 += (v[0][4 * j] * w[0] + v[0][4 * j + 1] * w[1]) + (v[0][4 * j + 2] * w[2] + v[0][4 * j + 3] * w[3]);
;                     s1 += (v[1][4 * j] * w[0] + v[1][4 * j + 1] * w[1]) + (v[1][4 * j + 2] * w[2] + v[1][4 * j + 3] * w[3]);
;                     s2 += (v[2][4 * j] * w[0] + v[2][4 * j + 1] * w[1]) + (v[2][4 * j + 2] * w[2] + v[2][4 * j + 3] * w[3]);
;                     s3 += (v[3][4 * j] * w[0] + v[3][4 * j + 1] * w[1]) + (v[3][4 * j + 2] * w[2] + v[3][4 * j + 3] * w[3]); }
;                 a[0][jc] = s0; a[1][jc] = s1; a[2][jc] = s2; a[3][jc] = s3;
;             }
	s_waitcnt lgkmcnt(8)
	v_lshlrev_b32_e32 v36, 16, v130
	v_and_b32_e32 v37, 0xffff0000, v130
	v_lshlrev_b32_e32 v38, 16, v131
	v_mfma_f32_16x16x4_f32 v[12:15], v36, v98, v[12:15]
	v_and_b32_e32 v39, 0xffff0000, v131
	v_mfma_f32_16x16x4_f32 v[16:19], v37, v99, v[16:19]
	v_lshlrev_b32_e32 v36, 16, v132
	v_mfma_f32_16x16x4_f32 v[12:15], v38, v100, v[12:15]
	v_and_b32_e32 v37, 0xffff0000, v132
	v_mfma_f32_16x16x4_f32 v[16:19], v39, v101, v[16:19]
	v_lshlrev_b32_e32 v38, 16, v133
	v_mfma_f32_16x16x4_f32 v[12:15], v36, v102, v[12:15]
	v_and_b32_e32 v39, 0xffff0000, v133
	v_mfma_f32_16x16x4_f32 v[16:19], v37, v103, v[16:19]
	v_lshlrev_b32_e32 v36, 16, v134
	v_mfma_f32_16x16x4_f32 v[12:15], v38, v104, v[12:15]
	v_and_b32_e32 v37, 0xffff0000, v134
	v_mfma_f32_16x16x4_f32 v[16:19], v39, v105, v[16:19]
	v_lshlrev_b32_e32 v38, 16, v135
	v_mfma_f32_16x16x4_f32 v[12:15], v36, v106, v[12:15]
	v_and_b32_e32 v39, 0xffff0000, v135
	v_mfma_f32_16x16x4_f32 v[16:19], v37, v107, v[16:19]
	v_lshlrev_b32_e32 v36, 16, v136
	v_mfma_f32_16x16x4_f32 v[12:15], v38, v108, v[12:15]
	v_and_b32_e32 v37, 0xffff0000, v136
	v_mfma_f32_16x16x4_f32 v[16:19], v39, v109, v[16:19]
	v_lshlrev_b32_e32 v38, 16, v137
	v_mfma_f32_16x16x4_f32 v[12:15], v36, v110, v[12:15]
	v_and_b32_e32 v39, 0xffff0000, v137
	v_mfma_f32_16x16x4_f32 v[16:19], v37, v111, v[16:19]
	v_lshlrev_b32_e32 v36, 16, v138
	v_mfma_f32_16x16x4_f32 v[12:15], v38, v112, v[12:15]
	v_and_b32_e32 v37, 0xffff0000, v138
	v_mfma_f32_16x16x4_f32 v[16:19], v39, v113, v[16:19]
	v_lshlrev_b32_e32 v38, 16, v139
	v_mfma_f32_16x16x4_f32 v[12:15], v36, v114, v[12:15]
	v_and_b32_e32 v39, 0xffff0000, v139
	v_mfma_f32_16x16x4_f32 v[16:19], v37, v115, v[16:19]
	v_lshlrev_b32_e32 v36, 16, v140
	v_mfma_f32_16x16x4_f32 v[12:15], v38, v116, v[12:15]
	v_and_b32_e32 v37, 0xffff0000, v140
	v_mfma_f32_16x16x4_f32 v[16:19], v39, v117, v[16:19]
	v_lshlrev_b32_e32 v38, 16, v141
	v_mfma_f32_16x16x4_f32 v[12:15], v36, v118, v[12:15]
	v_and_b32_e32 v39, 0xffff0000, v141
	v_mfma_f32_16x16x4_f32 v[16:19], v37, v119, v[16:19]
	v_lshlrev_b32_e32 v36, 16, v142
	v_mfma_f32_16x16x4_f32 v[12:15], v38, v120, v[12:15]
	v_and_b32_e32 v37, 0xffff0000, v142
	v_mfma_f32_16x16x4_f32 v[16:19], v39, v121, v[16:19]
	v_lshlrev_b32_e32 v38, 16, v143
	v_mfma_f32_16x16x4_f32 v[12:15], v36, v122, v[12:15]
	v_and_b32_e32 v39, 0xffff0000, v143
	v_mfma_f32_16x16x4_f32 v[16:19], v37, v123, v[16:19]
	v_lshlrev_b32_e32 v36, 16, v144
	v_mfma_f32_16x16x4_f32 v[12:15], v38, v124, v[12:15]
	v_and_b32_e32 v37, 0xffff0000, v144
	v_mfma_f32_16x16x4_f32 v[16:19], v39, v125, v[16:19]
	v_lshlrev_b32_e32 v38, 16, v145
	v_mfma_f32_16x16x4_f32 v[12:15], v36, v126, v[12:15]
	v_and_b32_e32 v39, 0xffff0000, v145
	v_mfma_f32_16x16x4_f32 v[16:19], v37, v127, v[16:19]
	s_nop 0
	v_mfma_f32_16x16x4_f32 v[12:15], v38, v128, v[12:15]
	s_nop 0
	v_mfma_f32_16x16x4_f32 v[16:19], v39, v129, v[16:19]
	ds_read_b128 v[98:101], v9 offset:896
	ds_read_b128 v[102:105], v9 offset:912
	ds_read_b128 v[106:109], v9 offset:928
	ds_read_b128 v[110:113], v9 offset:944
	ds_read_b128 v[114:117], v9 offset:960
	ds_read_b128 v[118:121], v9 offset:976
	ds_read_b128 v[122:125], v9 offset:992
	ds_read_b128 v[126:129], v9 offset:1008
	s_waitcnt vmcnt(4)
	s_waitcnt lgkmcnt(8)
; template <int NS>
; DI_ void skinny_pass_bf16(const bf16_t* XBrows, int nrows, const float* WsT, float* sk_out, int gw, int NGW, int lane) {
;     ...
;         for (int grp = 0; grp < NS / 8; ++grp) {
;             float a[4][8];
; #pragma unroll
;             for (int jc = 0; jc < 8; ++jc) {
;                 const float* wp = WsT + (8 * grp + jc) * WST + 4 * lane; float s0 = 0.f, s1 = 0.f, s2 = 0.f, s3 = 0.f;
; #pragma unroll
;                 for (int j = 0; j < 4; ++j) { const f32x4 w = *(const f32x4*)(wp + 256 * j);
;                     s0 += (v[0][4 * j] * w[0] + v[0][4 * j + 1] * w[1]) + (v[0][4 * j + 2] * w[2] + v[0][4 * j + 3] * w[3]);
;                     s1 += (v[1][4 * j] * w[0] + v[1][4 * j + 1] * w[1]) + (v[1][4 * j + 2] * w[2] + v[1][4 * j + 3] * w[3]);
;                     s2 += (v[2][4 * j] * w[0] + v[2][4 * j + 1] * w[1]) + (v[2][4 * j + 2] * w[2] + v[2][4 * j + 3] * w[3]);
;                     s3 += (v[3][4 * j] * w[0] + v[3][4 * j + 1] * w[1]) + (v[3][4 * j + 2] * w[2] + v[3][4 * j + 3] * w[3]); }
;                 a[0][jc] = s0; a[1][jc] = s1; a[2][jc] = s2; a[3][jc] = s3;
;             }
; #pragma unroll
;             for (int r = 0; r < 4; ++r) {
;                 { const bool up = (lane & 32) != 0;
; #pragma unroll
;                   for (int i = 0; i < 4; ++i) { const float send = up ? a[r][i] : a[r][4 + i], keep = up ? a[r][4 + i] : a[r][i]; a[r][i] = keep + __shfl_xor(send, 32); } }
;                 { const bool up = (lane & 16) != 0;
; #pragma unroll
;                   for (int i = 0; i < 2; ++i) { const float send = up ? a[r][i] : a[r][2 + i], keep = up ? a[r][2 + i] : a[r][i]; a[r][i] = keep + __shfl_xor(send, 16); } }
;                 { const bool up = (lane & 8) != 0; const float send = up ? a[r][0] : a[r][1], keep = up ? a[r][1] : a[r][0]; a[r][0] = keep + __shfl_xor(send, 8); }
;                 a[r][0] += __shfl_xor(a[r][0], 4); a[r][0] += __shfl_xor(a[r][0], 2); a[r][0] += __shfl_xor(a[r][0], 1);
;                 if ((lane & 7) == 0 && row + r * NGW < nrows) sk_out[(size_t)(row + r * NGW) * NS + 8 * grp + (lane >> 3)] = a[r][0];
	v_lshlrev_b32_e32 v36, 16, v20
	v_and_b32_e32 v37, 0xffff0000, v20
	v_lshlrev_b32_e32 v38, 16, v21
	v_mfma_f32_16x16x4_f32 v[12:15], v36, v66, v[12:15]
	v_and_b32_e32 v39, 0xffff0000, v21
	v_mfma_f32_16x16x4_f32 v[16:19], v37, v67, v[16:19]
	v_lshlrev_b32_e32 v36, 16, v22
	v_mfma_f32_16x16x4_f32 v[12:15], v38, v68, v[12:15]
	v_and_b32_e32 v37, 0xffff0000, v22
	v_mfma_f32_16x16x4_f32 v[16:19], v39, v69, v[16:19]
	v_lshlrev_b32_e32 v38, 16, v23
	v_mfma_f32_16x16x4_f32 v[12:15], v36, v70, v[12:15]
	v_and_b32_e32 v39, 0xffff0000, v23
	v_mfma_f32_16x16x4_f32 v[16:19], v37, v71, v[16:19]
	v_lshlrev_b32_e32 v36, 16, v24
	v_mfma_f32_16x16x4_f32 v[12:15], v38, v72, v[12:15]
	v_and_b32_e32 v37, 0xffff0000, v24
	v_mfma_f32_16x16x4_f32 v[16:19], v39, v73, v[16:19]
	v_lshlrev_b32_e32 v38, 16, v25
	v_mfma_f32_16x16x4_f32 v[12:15], v36, v74, v[12:15]
	v_and_b32_e32 v39, 0xffff0000, v25
	v_mfma_f32_16x16x4_f32 v[16:19], v37, v75, v[16:19]
	v_lshlrev_b32_e32 v36, 16, v26
	v_mfma_f32_16x16x4_f32 v[12:15], v38, v76, v[12:15]
	v_and_b32_e32 v37, 0xffff0000, v26
	v_mfma_f32_16x16x4_f32 v[16:19], v39, v77, v[16:19]
	v_lshlrev_b32_e32 v38, 16, v27
	v_mfma_f32_16x16x4_f32 v[12:15], v36, v78, v[12:15]
	v_and_b32_e32 v39, 0xffff0000, v27
	v_mfma_f32_16x16x4_f32 v[16:19], v37, v79, v[16:19]
	v_lshlrev_b32_e32 v36, 16, v28
	v_mfma_f32_16x16x4_f32 v[12:15], v38, v80, v[12:15]
	v_and_b32_e32 v37, 0xffff0000, v28
	v_mfma_f32_16x16x4_f32 v[16:19], v39, v81, v[16:19]
	v_lshlrev_b32_e32 v38, 16, v29
	v_mfma_f32_16x16x4_f32 v[12:15], v36, v82, v[12:15]
	v_and_b32_e32 v39, 0xffff0000, v29
	v_mfma_f32_16x16x4_f32 v[16:19], v37, v83, v[16:19]
	v_lshlrev_b32_e32 v36, 16, v30
	v_mfma_f32_16x16x4_f32 v[12:15], v38, v84, v[12:15]
	v_and_b32_e32 v37, 0xffff0000, v30
	v_mfma_f32_16x16x4_f32 v[16:19], v39, v85, v[16:19]
	v_lshlrev_b32_e32 v38, 16, v31
	v_mfma_f32_16x16x4_f32 v[12:15], v36, v86, v[12:15]
	v_and_b32_e32 v39, 0xffff0000, v31
	v_mfma_f32_16x16x4_f32 v[16:19], v37, v87, v[16:19]
	v_lshlrev_b32_e32 v36, 16, v32
	v_mfma_f32_16x16x4_f32 v[12:15], v38, v88, v[12:15]
	v_and_b32_e32 v37, 0xffff0000, v32
	v_mfma_f32_16x16x4_f32 v[16:19], v39, v89, v[16:19]
	v_lshlrev_b32_e32 v38, 16, v33
	v_mfma_f32_16x16x4_f32 v[12:15], v36, v90, v[12:15]
	v_and_b32_e32 v39, 0xffff0000, v33
	v_mfma_f32_16x16x4_f32 v[16:19], v37, v91, v[16:19]
	v_lshlrev_b32_e32 v36, 16, v34
	v_mfma_f32_16x16x4_f32 v[12:15], v38, v92, v[12:15]
	v_and_b32_e32 v37, 0xffff0000, v34
	v_mfma_f32_16x16x4_f32 v[16:19], v39, v93, v[16:19]
	v_lshlrev_b32_e32 v38, 16, v35
	v_mfma_f32_16x16x4_f32 v[12:15], v36, v94, v[12:15]
	v_and_b32_e32 v39, 0xffff0000, v35
	v_mfma_f32_16x16x4_f32 v[16:19], v37, v95, v[16:19]
	s_nop 0
	v_mfma_f32_16x16x4_f32 v[12:15], v38, v96, v[12:15]
	s_nop 0
	v_mfma_f32_16x16x4_f32 v[16:19], v39, v97, v[16:19]
	s_waitcnt vmcnt(0)
	s_waitcnt lgkmcnt(0)
	v_lshlrev_b32_e32 v36, 16, v50
	v_and_b32_e32 v37, 0xffff0000, v50
	v_lshlrev_b32_e32 v38, 16, v51
	v_mfma_f32_16x16x4_f32 v[12:15], v36, v98, v[12:15]
	v_and_b32_e32 v39, 0xffff0000, v51
	v_mfma_f32_16x16x4_f32 v[16:19], v37, v99, v[16:19]
	v_lshlrev_b32_e32 v36, 16, v52
	v_mfma_f32_16x16x4_f32 v[12:15], v38, v100, v[12:15]
	v_and_b32_e32 v37, 0xffff0000, v52
	v_mfma_f32_16x16x4_f32 v[16:19], v39, v101, v[16:19]
	v_lshlrev_b32_e32 v38, 16, v53
	v_mfma_f32_16x16x4_f32 v[12:15], v36, v102, v[12:15]
	v_and_b32_e32 v39, 0xffff0000, v53
	v_mfma_f32_16x16x4_f32 v[16:19], v37, v103, v[16:19]
	v_lshlrev_b32_e32 v36, 16, v54
	v_mfma_f32_16x16x4_f32 v[12:15], v38, v104, v[12:15]
	v_and_b32_e32 v37, 0xffff0000, v54
	v_mfma_f32_16x16x4_f32 v[16:19], v39, v105, v[16:19]
	v_lshlrev_b32_e32 v38, 16, v55
	v_mfma_f32_16x16x4_f32 v[12:15], v36, v106, v[12:15]
	v_and_b32_e32 v39, 0xffff0000, v55
	v_mfma_f32_16x16x4_f32 v[16:19], v37, v107, v[16:19]
	v_lshlrev_b32_e32 v36, 16, v56
	v_mfma_f32_16x16x4_f32 v[12:15], v38, v108, v[12:15]
	v_and_b32_e32 v37, 0xffff0000, v56
	v_mfma_f32_16x16x4_f32 v[16:19], v39, v109, v[16:19]
	v_lshlrev_b32_e32 v38, 16, v57
	v_mfma_f32_16x16x4_f32 v[12:15], v36, v110, v[12:15]
	v_and_b32_e32 v39, 0xffff0000, v57
	v_mfma_f32_16x16x4_f32 v[16:19], v37, v111, v[16:19]
	v_lshlrev_b32_e32 v36, 16, v58
	v_mfma_f32_16x16x4_f32 v[12:15], v38, v112, v[12:15]
	v_and_b32_e32 v37, 0xffff0000, v58
	v_mfma_f32_16x16x4_f32 v[16:19], v39, v113, v[16:19]
	v_lshlrev_b32_e32 v38, 16, v59
	v_mfma_f32_16x16x4_f32 v[12:15], v36, v114, v[12:15]
	v_and_b32_e32 v39, 0xffff0000, v59
	v_mfma_f32_16x16x4_f32 v[16:19], v37, v115, v[16:19]
	v_lshlrev_b32_e32 v36, 16, v60
	v_mfma_f32_16x16x4_f32 v[12:15], v38, v116, v[12:15]
	v_and_b32_e32 v37, 0xffff0000, v60
	v_mfma_f32_16x16x4_f32 v[16:19], v39, v117, v[16:19]
	v_lshlrev_b32_e32 v38, 16, v61
	v_mfma_f32_16x16x4_f32 v[12:15], v36, v118, v[12:15]
	v_and_b32_e32 v39, 0xffff0000, v61
	v_mfma_f32_16x16x4_f32 v[16:19], v37, v119, v[16:19]
	v_lshlrev_b32_e32 v36, 16, v62
	v_mfma_f32_16x16x4_f32 v[12:15], v38, v120, v[12:15]
	v_and_b32_e32 v37, 0xffff0000, v62
	v_mfma_f32_16x16x4_f32 v[16:19], v39, v121, v[16:19]
	v_lshlrev_b32_e32 v38, 16, v63
	v_mfma_f32_16x16x4_f32 v[12:15], v36, v122, v[12:15]
	v_and_b32_e32 v39, 0xffff0000, v63
	v_mfma_f32_16x16x4_f32 v[16:19], v37, v123, v[16:19]
	v_lshlrev_b32_e32 v36, 16, v64
	v_mfma_f32_16x16x4_f32 v[12:15], v38, v124, v[12:15]
	v_and_b32_e32 v37, 0xffff0000, v64
	v_mfma_f32_16x16x4_f32 v[16:19], v39, v125, v[16:19]
	v_lshlrev_b32_e32 v38, 16, v65
	v_mfma_f32_16x16x4_f32 v[12:15], v36, v126, v[12:15]
	v_and_b32_e32 v39, 0xffff0000, v65
	v_mfma_f32_16x16x4_f32 v[16:19], v37, v127, v[16:19]
	s_nop 0
	v_mfma_f32_16x16x4_f32 v[12:15], v38, v128, v[12:15]
	s_nop 0
	v_mfma_f32_16x16x4_f32 v[16:19], v39, v129, v[16:19]
	s_nop 15
	v_add_f32_e32 v12, v12, v16
	v_add_f32_e32 v13, v13, v17
	v_add_f32_e32 v14, v14, v18
	v_add_f32_e32 v15, v15, v19
	global_store_dword v[10:11], v12, off
	global_store_dword v[10:11], v13, off offset:128
	global_store_dword v[10:11], v14, off offset:256
	global_store_dword v[10:11], v15, off offset:384
	s_branch .LBB0_481
